# rwkv_wy: diagonal-block inversions with batched row prefetch (both passes), forward-substitution right-hand sides precomputed for all blocks, chunk-state lines touched ahead of their serialized loads
# speedup vs baseline: 1.2015x; 1.0046x over previous
.LBB0_573:
	v_add_u32_e32 v3, 0x100, v3
	s_movk_i32 s0, 0xeff
	v_cmp_lt_u32_e64 s[0:1], s0, v3
	ds_write_b32 v2, v1
	s_or_b64 s[24:25], s[0:1], s[24:25]
	v_add_u32_e32 v2, 0x400, v2
	s_andn2_b64 exec, exec, s[24:25]
	s_cbranch_execnz .LBB0_573
	s_or_b64 exec, exec, s[24:25]
	s_and_saveexec_b64 s[0:1], vcc
	s_cbranch_execz .LBB0_397
	v_lshlrev_b32_e32 v3, 6, v150
	v_and_b32_e32 v3, 0xc00, v3
	v_add_u32_e32 v3, v115, v3
	ds_read_b32 v192, v3 offset:64
	ds_read_b64 v[194:195], v3 offset:128
	ds_read_b96 v[196:198], v3 offset:192
	ds_read_b128 v[200:203], v3 offset:256
	ds_read_b128 v[204:207], v3 offset:320
	ds_read_b32 v208, v3 offset:336
	ds_read_b128 v[210:213], v3 offset:384
	ds_read_b64 v[214:215], v3 offset:400
	ds_read_b128 v[216:219], v3 offset:448
	ds_read_b96 v[220:222], v3 offset:464
	ds_read_b128 v[224:227], v3 offset:512
	ds_read_b128 v[228:231], v3 offset:528
	ds_read_b128 v[232:235], v3 offset:576
	ds_read_b128 v[236:239], v3 offset:592
	ds_read_b32 v240, v3 offset:608
	v_cmp_eq_u32_e32 vcc, 0, v149
	s_nop 1
	v_cndmask_b32_e64 v126, 0, 1.0, vcc
	v_cmp_eq_u32_e32 vcc, 1, v149
	s_nop 1
	v_cndmask_b32_e64 v127, 0, 1.0, vcc
	v_cmp_eq_u32_e32 vcc, 2, v149
	s_nop 1
	v_cndmask_b32_e64 v128, 0, 1.0, vcc
	v_cmp_eq_u32_e32 vcc, 3, v149
	s_nop 1
	v_cndmask_b32_e64 v129, 0, 1.0, vcc
	v_cmp_eq_u32_e32 vcc, 4, v149
	s_nop 1
	v_cndmask_b32_e64 v130, 0, 1.0, vcc
	v_cmp_eq_u32_e32 vcc, 5, v149
	s_nop 1
	v_cndmask_b32_e64 v131, 0, 1.0, vcc
	v_cmp_eq_u32_e32 vcc, 6, v149
	s_nop 1
	v_cndmask_b32_e64 v132, 0, 1.0, vcc
	v_cmp_eq_u32_e32 vcc, 7, v149
	s_nop 1
	v_cndmask_b32_e64 v133, 0, 1.0, vcc
	v_cmp_eq_u32_e32 vcc, 8, v149
	s_nop 1
	v_cndmask_b32_e64 v134, 0, 1.0, vcc
	v_cmp_eq_u32_e32 vcc, 9, v149
	s_nop 1
	v_cndmask_b32_e64 v135, 0, 1.0, vcc
	v_cmp_eq_u32_e32 vcc, 10, v149
	s_nop 1
	v_cndmask_b32_e64 v136, 0, 1.0, vcc
	v_cmp_eq_u32_e32 vcc, 11, v149
	s_nop 1
	v_cndmask_b32_e64 v137, 0, 1.0, vcc
	v_cmp_eq_u32_e32 vcc, 12, v149
	s_nop 1
	v_cndmask_b32_e64 v138, 0, 1.0, vcc
	v_cmp_eq_u32_e32 vcc, 13, v149
	s_nop 1
	v_cndmask_b32_e64 v139, 0, 1.0, vcc
	v_cmp_eq_u32_e32 vcc, 14, v149
	s_nop 1
	v_cndmask_b32_e64 v140, 0, 1.0, vcc
	v_cmp_eq_u32_e32 vcc, 15, v149
	s_nop 1
	v_cndmask_b32_e64 v141, 0, 1.0, vcc
	s_waitcnt lgkmcnt(7)
	v_fma_f32 v127, -v126, v192, v127
	v_fma_f32 v128, -v126, v194, v128
	v_fma_f32 v128, -v127, v195, v128
	v_fma_f32 v129, -v126, v196, v129
	v_fma_f32 v129, -v127, v197, v129
	v_fma_f32 v129, -v128, v198, v129
	v_fma_f32 v130, -v126, v200, v130
	v_fma_f32 v130, -v127, v201, v130
	v_fma_f32 v130, -v128, v202, v130
	v_fma_f32 v130, -v129, v203, v130
	v_fma_f32 v131, -v126, v204, v131
	v_fma_f32 v131, -v127, v205, v131
	v_fma_f32 v131, -v128, v206, v131
	v_fma_f32 v131, -v129, v207, v131
	v_fma_f32 v131, -v130, v208, v131
	v_fma_f32 v132, -v126, v210, v132
	v_fma_f32 v132, -v127, v211, v132
	v_fma_f32 v132, -v128, v212, v132
	v_fma_f32 v132, -v129, v213, v132
	v_fma_f32 v132, -v130, v214, v132
	v_fma_f32 v132, -v131, v215, v132
	ds_read_b128 v[192:195], v3 offset:640
	ds_read_b128 v[196:199], v3 offset:656
	ds_read_b64 v[200:201], v3 offset:672
	ds_read_b128 v[202:205], v3 offset:704
	ds_read_b128 v[206:209], v3 offset:720
	ds_read_b96 v[210:212], v3 offset:736
	s_waitcnt lgkmcnt(6)
	v_fma_f32 v133, -v126, v216, v133
	v_fma_f32 v133, -v127, v217, v133
	v_fma_f32 v133, -v128, v218, v133
	v_fma_f32 v133, -v129, v219, v133
	v_fma_f32 v133, -v130, v220, v133
	v_fma_f32 v133, -v131, v221, v133
	v_fma_f32 v133, -v132, v222, v133
	v_fma_f32 v134, -v126, v224, v134
	v_fma_f32 v134, -v127, v225, v134
	v_fma_f32 v134, -v128, v226, v134
	v_fma_f32 v134, -v129, v227, v134
	v_fma_f32 v134, -v130, v228, v134
	v_fma_f32 v134, -v131, v229, v134
	v_fma_f32 v134, -v132, v230, v134
	v_fma_f32 v134, -v133, v231, v134
	v_fma_f32 v135, -v126, v232, v135
	v_fma_f32 v135, -v127, v233, v135
	v_fma_f32 v135, -v128, v234, v135
	v_fma_f32 v135, -v129, v235, v135
	v_fma_f32 v135, -v130, v236, v135
	v_fma_f32 v135, -v131, v237, v135
	v_fma_f32 v135, -v132, v238, v135
	v_fma_f32 v135, -v133, v239, v135
	v_fma_f32 v135, -v134, v240, v135
	ds_read_b128 v[216:219], v3 offset:768
	ds_read_b128 v[220:223], v3 offset:784
	ds_read_b128 v[224:227], v3 offset:800
	ds_read_b128 v[228:231], v3 offset:832
	ds_read_b128 v[232:235], v3 offset:848
	ds_read_b128 v[236:239], v3 offset:864
	ds_read_b32 v240, v3 offset:880
	s_waitcnt lgkmcnt(7)
	v_fma_f32 v136, -v126, v192, v136
	v_fma_f32 v136, -v127, v193, v136
	v_fma_f32 v136, -v128, v194, v136
	v_fma_f32 v136, -v129, v195, v136
	v_fma_f32 v136, -v130, v196, v136
	v_fma_f32 v136, -v131, v197, v136
	v_fma_f32 v136, -v132, v198, v136
	v_fma_f32 v136, -v133, v199, v136
	v_fma_f32 v136, -v134, v200, v136
	v_fma_f32 v136, -v135, v201, v136
	v_fma_f32 v137, -v126, v202, v137
	v_fma_f32 v137, -v127, v203, v137
	v_fma_f32 v137, -v128, v204, v137
	v_fma_f32 v137, -v129, v205, v137
	v_fma_f32 v137, -v130, v206, v137
	v_fma_f32 v137, -v131, v207, v137
	v_fma_f32 v137, -v132, v208, v137
	v_fma_f32 v137, -v133, v209, v137
	v_fma_f32 v137, -v134, v210, v137
	v_fma_f32 v137, -v135, v211, v137
	v_fma_f32 v137, -v136, v212, v137
	ds_read_b128 v[192:195], v3 offset:896
	ds_read_b128 v[196:199], v3 offset:912
	ds_read_b128 v[200:203], v3 offset:928
	ds_read_b64 v[204:205], v3 offset:944
	s_waitcnt lgkmcnt(4)
	v_fma_f32 v138, -v126, v216, v138
	v_fma_f32 v138, -v127, v217, v138
	v_fma_f32 v138, -v128, v218, v138
	v_fma_f32 v138, -v129, v219, v138
	v_fma_f32 v138, -v130, v220, v138
	v_fma_f32 v138, -v131, v221, v138
	v_fma_f32 v138, -v132, v222, v138
	v_fma_f32 v138, -v133, v223, v138
	v_fma_f32 v138, -v134, v224, v138
	v_fma_f32 v138, -v135, v225, v138
	v_fma_f32 v138, -v136, v226, v138
	v_fma_f32 v138, -v137, v227, v138
	v_fma_f32 v139, -v126, v228, v139
	v_fma_f32 v139, -v127, v229, v139
	v_fma_f32 v139, -v128, v230, v139
	v_fma_f32 v139, -v129, v231, v139
	v_fma_f32 v139, -v130, v232, v139
	v_fma_f32 v139, -v131, v233, v139
	v_fma_f32 v139, -v132, v234, v139
	v_fma_f32 v139, -v133, v235, v139
	v_fma_f32 v139, -v134, v236, v139
	v_fma_f32 v139, -v135, v237, v139
	v_fma_f32 v139, -v136, v238, v139
	v_fma_f32 v139, -v137, v239, v139
	v_fma_f32 v139, -v138, v240, v139
	ds_read_b128 v[216:219], v3 offset:960
	ds_read_b128 v[220:223], v3 offset:976
	ds_read_b128 v[224:227], v3 offset:992
	ds_read_b96 v[228:230], v3 offset:1008
	s_waitcnt lgkmcnt(4)
	v_fma_f32 v140, -v126, v192, v140
	v_fma_f32 v140, -v127, v193, v140
	v_fma_f32 v140, -v128, v194, v140
	v_fma_f32 v140, -v129, v195, v140
	v_fma_f32 v140, -v130, v196, v140
	v_fma_f32 v140, -v131, v197, v140
	v_fma_f32 v140, -v132, v198, v140
	v_fma_f32 v140, -v133, v199, v140
	v_fma_f32 v140, -v134, v200, v140
	v_fma_f32 v140, -v135, v201, v140
	v_fma_f32 v140, -v136, v202, v140
	v_fma_f32 v140, -v137, v203, v140
	v_fma_f32 v140, -v138, v204, v140
	v_fma_f32 v140, -v139, v205, v140
	s_waitcnt lgkmcnt(0)
	v_fma_f32 v141, -v126, v216, v141
	v_fma_f32 v141, -v127, v217, v141
	v_fma_f32 v141, -v128, v218, v141
	v_fma_f32 v141, -v129, v219, v141
	v_fma_f32 v141, -v130, v220, v141
	v_fma_f32 v141, -v131, v221, v141
	v_fma_f32 v141, -v132, v222, v141
	v_fma_f32 v141, -v133, v223, v141
	v_fma_f32 v141, -v134, v224, v141
	v_fma_f32 v141, -v135, v225, v141
	v_fma_f32 v141, -v136, v226, v141
	v_fma_f32 v141, -v137, v227, v141
	v_fma_f32 v141, -v138, v228, v141
	v_fma_f32 v141, -v139, v229, v141
	v_fma_f32 v141, -v140, v230, v141
	v_lshl_add_u32 v3, v149, 2, v3
	s_waitcnt lgkmcnt(0)
	ds_write2_b32 v3, v126, v127 offset0:0 offset1:16
	ds_write2_b32 v3, v128, v129 offset0:32 offset1:48
	ds_write2_b32 v3, v130, v131 offset0:64 offset1:80
	ds_write2_b32 v3, v132, v133 offset0:96 offset1:112
	ds_write2_b32 v3, v134, v135 offset0:128 offset1:144
	ds_write2_b32 v3, v136, v137 offset0:160 offset1:176
	ds_write2_b32 v3, v138, v139 offset0:192 offset1:208
	ds_write2_b32 v3, v140, v141 offset0:224 offset1:240
	s_branch .LBB0_397

.LBB0_856:
	s_or_b64 exec, exec, s[0:1]
	v_bfe_u32 v108, v196, 6, 1
	v_ashrrev_i32_e32 v110, 7, v196
	s_mov_b32 s0, 0x13000
	v_mad_u32_u24 v94, v108, s0, 0
	v_lshlrev_b32_e32 v95, 12, v110
	v_lshlrev_b32_e32 v109, 2, v199
	s_waitcnt lgkmcnt(0)
	s_barrier
	s_ashr_i32 s80, s72, 3
	v_readlane_b32 s81, v255, 20
	v_lshrrev_b32_e32 v228, 8, v177
	s_ashr_i32 s82, s80, s81
	s_and_b32 s83, s80, s62
	s_lshl_b32 s82, s82, 3
	s_or_b32 s82, s82, s74
	s_lshl_b32 s82, s82, 1
	v_readfirstlane_b32 s84, v228
	v_readlane_b32 s86, v253, 7
	v_readlane_b32 s87, v253, 8
	v_and_b32_e32 v228, 31, v177
	v_bfe_u32 v229, v177, 6, 2
	s_add_u32 s82, s82, s84
	s_lshl_b32 s82, s82, s81
	s_sub_u32 s85, s62, s83
	s_cmp_eq_u32 s84, 0
	s_cselect_b32 s83, s83, s85
	s_add_u32 s82, s82, s83
	s_lshr_b32 s85, s82, 17
	s_lshl_b32 s84, s82, 15
	s_add_u32 s86, s86, s84
	s_addc_u32 s87, s87, s85
	v_lshl_or_b32 v228, v229, 5, v228
	v_lshlrev_b32_e32 v228, 7, v228
	global_load_dword v229, v228, s[86:87]
	v_add3_u32 v111, v94, v95, v109
	ds_read2st64_b32 v[94:95], v111 offset0:192 offset1:193
	ds_read2st64_b32 v[96:97], v111 offset0:194 offset1:195
	v_lshlrev_b32_e32 v144, 10, v108
	v_readlane_b32 s0, v254, 53
	v_ashrrev_i32_e32 v0, 8, v196
	s_waitcnt lgkmcnt(1)
	v_add_f32_e32 v95, v94, v95
	s_waitcnt lgkmcnt(0)
	v_add_f32_e32 v112, v96, v95
	v_add_f32_e32 v113, v97, v112
	ds_read2st64_b32 v[96:97], v111 offset0:196 offset1:197
	v_cmp_eq_u32_e32 vcc, 1, v0
	v_lshlrev_b32_e32 v166, 2, v192
	s_waitcnt lgkmcnt(0)
	v_add_f32_e32 v114, v96, v113
	v_add_f32_e32 v115, v97, v114
	ds_read2st64_b32 v[96:97], v111 offset0:198 offset1:199
	s_waitcnt lgkmcnt(0)
	v_add_f32_e32 v116, v96, v115
	v_add_f32_e32 v117, v97, v116
	ds_read2st64_b32 v[96:97], v111 offset0:200 offset1:201
	s_waitcnt lgkmcnt(0)
	v_add_f32_e32 v118, v96, v117
	v_add_f32_e32 v119, v97, v118
	ds_read2st64_b32 v[96:97], v111 offset0:202 offset1:203
	s_waitcnt lgkmcnt(0)
	v_add_f32_e32 v120, v96, v119
	v_add_f32_e32 v121, v97, v120
	ds_read2st64_b32 v[96:97], v111 offset0:204 offset1:205
	s_waitcnt lgkmcnt(0)
	v_add_f32_e32 v122, v96, v121
	v_add_f32_e32 v123, v97, v122
	ds_read2st64_b32 v[96:97], v111 offset0:206 offset1:207
	s_waitcnt lgkmcnt(0)
	v_add_f32_e32 v142, v96, v123
	v_add_f32_e32 v143, v97, v142
	v_lshlrev_b32_e32 v96, 8, v110
	v_add_u32_e32 v97, s0, v144
	v_add3_u32 v96, v97, v96, v109
	ds_write_b32 v96, v143
	s_and_saveexec_b64 s[0:1], vcc
	s_cbranch_execz .LBB0_865
	v_lshlrev_b32_e32 v96, 10, v194
	v_lshl_or_b32 v96, v198, 12, v96
	s_add_i32 s4, 0, 0x11000
	v_add3_u32 v145, s4, v166, v96
	ds_read2_b32 v[98:99], v145 offset1:16
	ds_read2_b32 v[104:105], v145 offset0:64 offset1:80
	ds_read2_b32 v[146:147], v145 offset0:32 offset1:48
	ds_read2_b32 v[100:101], v145 offset0:128 offset1:144
	ds_read2_b32 v[96:97], v145 offset0:192 offset1:208
	s_waitcnt lgkmcnt(4)
	v_fma_f32 v148, v68, v98, 0
	v_fmac_f32_e32 v148, v64, v99
	s_waitcnt lgkmcnt(2)
	v_fmac_f32_e32 v148, v72, v146
	v_and_b32_e32 v146, 64, v179
	ds_read2_b32 v[106:107], v145 offset0:96 offset1:112
	ds_read2_b32 v[102:103], v145 offset0:160 offset1:176
	ds_read2_b32 v[98:99], v145 offset0:224 offset1:240
	v_xor_b32_e32 v145, 1, v179
	v_add_u32_e32 v149, 64, v146
	v_cmp_lt_i32_e32 vcc, v145, v149
	v_fmac_f32_e32 v148, v76, v147
	v_xor_b32_e32 v146, 2, v179
	v_cndmask_b32_e32 v145, v179, v145, vcc
	v_lshlrev_b32_e32 v145, 2, v145
	s_nop 1
	v_mov_b32_dpp v147, v148 quad_perm:[1,0,3,2] row_mask:0xf bank_mask:0xf
	v_cmp_lt_i32_e32 vcc, v146, v149
	v_xor_b32_e32 v153, 8, v179
	v_readlane_b32 s4, v254, 59
	v_cndmask_b32_e32 v146, v179, v146, vcc
	v_lshlrev_b32_e32 v146, 2, v146
	s_waitcnt lgkmcnt(0)
	v_add_f32_e32 v148, v148, v147
	s_nop 1
	v_mov_b32_dpp v152, v148 quad_perm:[2,3,0,1] row_mask:0xf bank_mask:0xf
	v_xor_b32_e32 v147, 4, v179
	v_cmp_lt_i32_e32 vcc, v147, v149
	s_waitcnt lgkmcnt(0)
	v_add_f32_e32 v148, v148, v152
	v_cndmask_b32_e32 v147, v179, v147, vcc
	v_lshlrev_b32_e32 v147, 2, v147
	s_nop 1
	v_mov_b32_dpp v152, v148 row_shl:4 row_mask:0xf bank_mask:0x5
	s_nop 1
	v_mov_b32_dpp v152, v148 row_shr:4 row_mask:0xf bank_mask:0xa
	v_cmp_lt_i32_e32 vcc, v153, v149
	s_waitcnt lgkmcnt(0)
	v_add_f32_e32 v152, v148, v152
	v_cndmask_b32_e32 v149, v179, v153, vcc
	v_lshlrev_b32_e32 v149, 2, v149
	s_nop 1
	v_mov_b32_dpp v153, v152 row_shl:8 row_mask:0xf bank_mask:0x3
	s_nop 1
	v_mov_b32_dpp v153, v152 row_shr:8 row_mask:0xf bank_mask:0xc
	v_lshl_add_u32 v148, v198, 6, s4
	v_cmp_eq_u32_e32 vcc, 0, v192
	v_add_u32_e32 v148, v148, v200
	s_and_saveexec_b64 s[24:25], vcc
	s_cbranch_execz .LBB0_859
	s_waitcnt lgkmcnt(0)
	v_add_f32_e32 v152, v152, v153
	ds_write_b32 v148, v152

.LBB0_1030:
	s_andn2_saveexec_b64 s[24:25], s[24:25]
	v_mov_b32_e32 v2, 0
	v_mov_b32_e32 v3, v2
	ds_write_b128 v204, v[88:91]
	s_or_b64 exec, exec, s[24:25]
	v_mfma_f32_16x16x32_bf16 v[88:91], v[108:111], v[84:87], 0
	v_cndmask_b32_e64 v96, -v96, 0, s[38:39]
	v_cndmask_b32_e64 v97, 0, -v97, s[0:1]
	v_cmp_gt_u32_e64 s[0:1], v123, v197
	v_mfma_f32_16x16x32_bf16 v[84:87], v[116:119], v[84:87], 0
	v_cmp_gt_u32_e64 s[38:39], v173, v197
	v_cndmask_b32_e64 v98, -v98, 0, s[40:41]
	v_cndmask_b32_e64 v99, -v99, 0, s[42:43]
	v_mfma_f32_16x16x32_bf16 v[88:91], v[112:115], v[80:83], v[88:91]
	v_cmp_gt_u32_e64 s[40:41], v174, v197
	v_cmp_gt_u32_e64 s[42:43], v170, v197
	v_cndmask_b32_e64 v100, -v100, 0, s[44:45]
	v_mfma_f32_16x16x32_bf16 v[80:83], v[92:95], v[80:83], v[84:87]
	v_cndmask_b32_e64 v101, -v101, 0, s[46:47]
	v_cndmask_b32_e64 v102, -v102, 0, s[48:49]
	v_cndmask_b32_e64 v103, -v103, 0, s[50:51]
	s_nop 0
	v_cndmask_b32_e64 v84, v88, 0, s[0:1]
	v_cndmask_b32_e64 v85, v89, 0, s[38:39]
	v_cndmask_b32_e64 v86, v90, 0, s[40:41]
	v_cndmask_b32_e64 v87, v91, 0, s[42:43]
	v_cvt_pk_bf16_f32 v84, v84, v85
	v_cvt_pk_bf16_f32 v85, v86, v87
	ds_write2st64_b64 v205, v[84:85], v[2:3] offset0:64 offset1:96
	v_and_b32_e32 v2, 0xff, v196
	v_lshl_add_u32 v2, v2, 2, v181
	v_cndmask_b32_e64 v84, -v80, 0, s[0:1]
	v_lshl_add_u32 v86, v143, 1, v201
	v_lshlrev_b32_e32 v80, 4, v202
	s_waitcnt lgkmcnt(0)
	s_barrier
	ds_write2st64_b32 v2, v1, v1 offset0:32 offset1:36
	ds_write2st64_b32 v2, v1, v1 offset0:40 offset1:44
	ds_write2st64_b32 v2, v1, v1 offset0:48 offset1:52
	ds_write2st64_b32 v2, v1, v1 offset0:56 offset1:60
	v_cvt_pk_bf16_f32 v2, v96, v97
	v_add_u32_e32 v91, v86, v80
	v_lshlrev_b32_e32 v80, 4, v203
	v_cvt_pk_bf16_f32 v3, v98, v99
	ds_write_b64 v91, v[2:3] offset:16384
	v_cvt_pk_bf16_f32 v2, v100, v101
	v_add_u32_e32 v90, v86, v80
	v_cvt_pk_bf16_f32 v3, v102, v103
	ds_write_b64 v90, v[2:3] offset:16384
	v_lshlrev_b32_e32 v2, 4, v207
	v_add_u32_e32 v3, v86, v2
	v_lshlrev_b32_e32 v2, 4, v122
	v_cndmask_b32_e64 v104, -v104, 0, s[52:53]
	v_cndmask_b32_e64 v105, -v105, 0, s[54:55]
	v_cndmask_b32_e64 v106, -v106, 0, s[56:57]
	v_cndmask_b32_e64 v107, -v107, 0, s[58:59]
	v_cndmask_b32_e64 v85, -v81, 0, s[38:39]
	v_cvt_pk_bf16_f32 v80, v104, v105
	v_cvt_pk_bf16_f32 v81, v106, v107
	v_add_u32_e32 v2, v86, v2
	v_cndmask_b32_e64 v82, -v82, 0, s[40:41]
	v_cndmask_b32_e64 v83, -v83, 0, s[42:43]
	ds_write_b64 v3, v[80:81] offset:16384
	v_cvt_pk_bf16_f32 v80, v84, v85
	v_cvt_pk_bf16_f32 v81, v82, v83
	ds_write_b64 v2, v[80:81] offset:16384
	s_and_saveexec_b64 s[0:1], vcc
	s_cbranch_execz .LBB0_1034
	v_lshlrev_b32_e32 v81, 6, v196
	v_and_b32_e32 v81, 0xc00, v81
	v_add_u32_e32 v81, v199, v81
	ds_read_b32 v204, v81 offset:64
	ds_read_b64 v[206:207], v81 offset:128
	ds_read_b96 v[208:210], v81 offset:192
	ds_read_b128 v[212:215], v81 offset:256
	ds_read_b128 v[216:219], v81 offset:320
	ds_read_b32 v220, v81 offset:336
	ds_read_b128 v[222:225], v81 offset:384
	ds_read_b64 v[226:227], v81 offset:400
	ds_read_b128 v[92:95], v81 offset:448
	ds_read_b96 v[96:98], v81 offset:464
	ds_read_b128 v[100:103], v81 offset:512
	ds_read_b128 v[104:107], v81 offset:528
	ds_read_b128 v[108:111], v81 offset:576
	ds_read_b128 v[112:115], v81 offset:592
	ds_read_b32 v116, v81 offset:608
	v_cmp_eq_u32_e32 vcc, 0, v192
	s_nop 1
	v_cndmask_b32_e64 v236, 0, 1.0, vcc
	v_cmp_eq_u32_e32 vcc, 1, v192
	s_nop 1
	v_cndmask_b32_e64 v237, 0, 1.0, vcc
	v_cmp_eq_u32_e32 vcc, 2, v192
	s_nop 1
	v_cndmask_b32_e64 v238, 0, 1.0, vcc
	v_cmp_eq_u32_e32 vcc, 3, v192
	s_nop 1
	v_cndmask_b32_e64 v239, 0, 1.0, vcc
	v_cmp_eq_u32_e32 vcc, 4, v192
	s_nop 1
	v_cndmask_b32_e64 v240, 0, 1.0, vcc
	v_cmp_eq_u32_e32 vcc, 5, v192
	s_nop 1
	v_cndmask_b32_e64 v241, 0, 1.0, vcc
	v_cmp_eq_u32_e32 vcc, 6, v192
	s_nop 1
	v_cndmask_b32_e64 v242, 0, 1.0, vcc
	v_cmp_eq_u32_e32 vcc, 7, v192
	s_nop 1
	v_cndmask_b32_e64 v243, 0, 1.0, vcc
	v_cmp_eq_u32_e32 vcc, 8, v192
	s_nop 1
	v_cndmask_b32_e64 v244, 0, 1.0, vcc
	v_cmp_eq_u32_e32 vcc, 9, v192
	s_nop 1
	v_cndmask_b32_e64 v245, 0, 1.0, vcc
	v_cmp_eq_u32_e32 vcc, 10, v192
	s_nop 1
	v_cndmask_b32_e64 v246, 0, 1.0, vcc
	v_cmp_eq_u32_e32 vcc, 11, v192
	s_nop 1
	v_cndmask_b32_e64 v247, 0, 1.0, vcc
	v_cmp_eq_u32_e32 vcc, 12, v192
	s_nop 1
	v_cndmask_b32_e64 v248, 0, 1.0, vcc
	v_cmp_eq_u32_e32 vcc, 13, v192
	s_nop 1
	v_cndmask_b32_e64 v249, 0, 1.0, vcc
	v_cmp_eq_u32_e32 vcc, 14, v192
	s_nop 1
	v_cndmask_b32_e64 v250, 0, 1.0, vcc
	v_cmp_eq_u32_e32 vcc, 15, v192
	s_nop 1
	v_cndmask_b32_e64 v251, 0, 1.0, vcc
	s_waitcnt lgkmcnt(7)
	v_fma_f32 v237, -v236, v204, v237
	v_fma_f32 v238, -v236, v206, v238
	v_fma_f32 v238, -v237, v207, v238
	v_fma_f32 v239, -v236, v208, v239
	v_fma_f32 v239, -v237, v209, v239
	v_fma_f32 v239, -v238, v210, v239
	v_fma_f32 v240, -v236, v212, v240
	v_fma_f32 v240, -v237, v213, v240
	v_fma_f32 v240, -v238, v214, v240
	v_fma_f32 v240, -v239, v215, v240
	v_fma_f32 v241, -v236, v216, v241
	v_fma_f32 v241, -v237, v217, v241
	v_fma_f32 v241, -v238, v218, v241
	v_fma_f32 v241, -v239, v219, v241
	v_fma_f32 v241, -v240, v220, v241
	v_fma_f32 v242, -v236, v222, v242
	v_fma_f32 v242, -v237, v223, v242
	v_fma_f32 v242, -v238, v224, v242
	v_fma_f32 v242, -v239, v225, v242
	v_fma_f32 v242, -v240, v226, v242
	v_fma_f32 v242, -v241, v227, v242
	ds_read_b128 v[204:207], v81 offset:640
	ds_read_b128 v[208:211], v81 offset:656
	ds_read_b64 v[212:213], v81 offset:672
	ds_read_b128 v[214:217], v81 offset:704
	ds_read_b128 v[218:221], v81 offset:720
	ds_read_b96 v[222:224], v81 offset:736
	s_waitcnt lgkmcnt(6)
	v_fma_f32 v243, -v236, v92, v243
	v_fma_f32 v243, -v237, v93, v243
	v_fma_f32 v243, -v238, v94, v243
	v_fma_f32 v243, -v239, v95, v243
	v_fma_f32 v243, -v240, v96, v243
	v_fma_f32 v243, -v241, v97, v243
	v_fma_f32 v243, -v242, v98, v243
	v_fma_f32 v244, -v236, v100, v244
	v_fma_f32 v244, -v237, v101, v244
	v_fma_f32 v244, -v238, v102, v244
	v_fma_f32 v244, -v239, v103, v244
	v_fma_f32 v244, -v240, v104, v244
	v_fma_f32 v244, -v241, v105, v244
	v_fma_f32 v244, -v242, v106, v244
	v_fma_f32 v244, -v243, v107, v244
	v_fma_f32 v245, -v236, v108, v245
	v_fma_f32 v245, -v237, v109, v245
	v_fma_f32 v245, -v238, v110, v245
	v_fma_f32 v245, -v239, v111, v245
	v_fma_f32 v245, -v240, v112, v245
	v_fma_f32 v245, -v241, v113, v245
	v_fma_f32 v245, -v242, v114, v245
	v_fma_f32 v245, -v243, v115, v245
	v_fma_f32 v245, -v244, v116, v245
	ds_read_b128 v[92:95], v81 offset:768
	ds_read_b128 v[96:99], v81 offset:784
	ds_read_b128 v[100:103], v81 offset:800
	ds_read_b128 v[104:107], v81 offset:832
	ds_read_b128 v[108:111], v81 offset:848
	ds_read_b128 v[112:115], v81 offset:864
	ds_read_b32 v116, v81 offset:880
	s_waitcnt lgkmcnt(7)
	v_fma_f32 v246, -v236, v204, v246
	v_fma_f32 v246, -v237, v205, v246
	v_fma_f32 v246, -v238, v206, v246
	v_fma_f32 v246, -v239, v207, v246
	v_fma_f32 v246, -v240, v208, v246
	v_fma_f32 v246, -v241, v209, v246
	v_fma_f32 v246, -v242, v210, v246
	v_fma_f32 v246, -v243, v211, v246
	v_fma_f32 v246, -v244, v212, v246
	v_fma_f32 v246, -v245, v213, v246
	v_fma_f32 v247, -v236, v214, v247
	v_fma_f32 v247, -v237, v215, v247
	v_fma_f32 v247, -v238, v216, v247
	v_fma_f32 v247, -v239, v217, v247
	v_fma_f32 v247, -v240, v218, v247
	v_fma_f32 v247, -v241, v219, v247
	v_fma_f32 v247, -v242, v220, v247
	v_fma_f32 v247, -v243, v221, v247
	v_fma_f32 v247, -v244, v222, v247
	v_fma_f32 v247, -v245, v223, v247
	v_fma_f32 v247, -v246, v224, v247
	ds_read_b128 v[204:207], v81 offset:896
	ds_read_b128 v[208:211], v81 offset:912
	ds_read_b128 v[212:215], v81 offset:928
	ds_read_b64 v[216:217], v81 offset:944
	s_waitcnt lgkmcnt(4)
	v_fma_f32 v248, -v236, v92, v248
	v_fma_f32 v248, -v237, v93, v248
	v_fma_f32 v248, -v238, v94, v248
	v_fma_f32 v248, -v239, v95, v248
	v_fma_f32 v248, -v240, v96, v248
	v_fma_f32 v248, -v241, v97, v248
	v_fma_f32 v248, -v242, v98, v248
	v_fma_f32 v248, -v243, v99, v248
	v_fma_f32 v248, -v244, v100, v248
	v_fma_f32 v248, -v245, v101, v248
	v_fma_f32 v248, -v246, v102, v248
	v_fma_f32 v248, -v247, v103, v248
	v_fma_f32 v249, -v236, v104, v249
	v_fma_f32 v249, -v237, v105, v249
	v_fma_f32 v249, -v238, v106, v249
	v_fma_f32 v249, -v239, v107, v249
	v_fma_f32 v249, -v240, v108, v249
	v_fma_f32 v249, -v241, v109, v249
	v_fma_f32 v249, -v242, v110, v249
	v_fma_f32 v249, -v243, v111, v249
	v_fma_f32 v249, -v244, v112, v249
	v_fma_f32 v249, -v245, v113, v249
	v_fma_f32 v249, -v246, v114, v249
	v_fma_f32 v249, -v247, v115, v249
	v_fma_f32 v249, -v248, v116, v249
	ds_read_b128 v[92:95], v81 offset:960
	ds_read_b128 v[96:99], v81 offset:976
	ds_read_b128 v[100:103], v81 offset:992
	ds_read_b96 v[104:106], v81 offset:1008
	s_waitcnt lgkmcnt(4)
	v_fma_f32 v250, -v236, v204, v250
	v_fma_f32 v250, -v237, v205, v250
	v_fma_f32 v250, -v238, v206, v250
	v_fma_f32 v250, -v239, v207, v250
	v_fma_f32 v250, -v240, v208, v250
	v_fma_f32 v250, -v241, v209, v250
	v_fma_f32 v250, -v242, v210, v250
	v_fma_f32 v250, -v243, v211, v250
	v_fma_f32 v250, -v244, v212, v250
	v_fma_f32 v250, -v245, v213, v250
	v_fma_f32 v250, -v246, v214, v250
	v_fma_f32 v250, -v247, v215, v250
	v_fma_f32 v250, -v248, v216, v250
	v_fma_f32 v250, -v249, v217, v250
	s_waitcnt lgkmcnt(0)
	v_fma_f32 v251, -v236, v92, v251
	v_fma_f32 v251, -v237, v93, v251
	v_fma_f32 v251, -v238, v94, v251
	v_fma_f32 v251, -v239, v95, v251
	v_fma_f32 v251, -v240, v96, v251
	v_fma_f32 v251, -v241, v97, v251
	v_fma_f32 v251, -v242, v98, v251
	v_fma_f32 v251, -v243, v99, v251
	v_fma_f32 v251, -v244, v100, v251
	v_fma_f32 v251, -v245, v101, v251
	v_fma_f32 v251, -v246, v102, v251
	v_fma_f32 v251, -v247, v103, v251
	v_fma_f32 v251, -v248, v104, v251
	v_fma_f32 v251, -v249, v105, v251
	v_fma_f32 v251, -v250, v106, v251
	v_lshl_add_u32 v81, v192, 2, v81
	s_waitcnt lgkmcnt(0)
	ds_write2_b32 v81, v236, v237 offset0:0 offset1:16
	ds_write2_b32 v81, v238, v239 offset0:32 offset1:48
	ds_write2_b32 v81, v240, v241 offset0:64 offset1:80
	ds_write2_b32 v81, v242, v243 offset0:96 offset1:112
	ds_write2_b32 v81, v244, v245 offset0:128 offset1:144
	ds_write2_b32 v81, v246, v247 offset0:160 offset1:176
	ds_write2_b32 v81, v248, v249 offset0:192 offset1:208
	ds_write2_b32 v81, v250, v251 offset0:224 offset1:240
.LBB0_1034:
	s_or_b64 exec, exec, s[0:1]
	s_ashr_i32 s4, s72, 3
	v_readlane_b32 s6, v255, 20
	s_ashr_i32 s0, s4, s6
	s_and_b32 s1, s4, s62
	s_sub_i32 s5, s62, s1
	v_mov_b32_e32 v81, s1
	s_lshl_b32 s0, s0, 4
	s_lshl_b32 s1, s74, 1
	v_mov_b32_e32 v80, s5
	s_or_b32 s0, s0, s1
	v_cndmask_b32_e64 v80, v80, v81, s[36:37]
	v_add_u32_e32 v0, s0, v0
	v_lshl_add_u32 v80, v0, s6, v80
	v_ashrrev_i32_e32 v81, 31, v80
	v_readlane_b32 s0, v253, 7
	v_lshlrev_b64 v[80:81], 15, v[80:81]
	v_readlane_b32 s1, v253, 8
	v_lshlrev_b32_e32 v0, 2, v200
	v_mov_b32_e32 v143, v1
	v_lshl_add_u64 v[88:89], s[0:1], 0, v[80:81]
	v_lshl_add_u64 v[80:81], v[88:89], 0, v[0:1]
	v_lshl_add_u64 v[86:87], v[80:81], 0, v[142:143]
	global_load_dwordx4 v[82:85], v[86:87], off offset:16
	global_load_dwordx4 v[92:95], v[86:87], off
	v_lshl_add_u32 v0, v195, 2, v181
	s_mov_b32 s0, 0x11000
	v_add3_u32 v107, v0, v166, s0
	v_lshl_add_u32 v0, v194, 2, v199
	v_or_b32_e32 v106, 4, v194
	s_add_i32 s72, s72, s78
	s_cmpk_gt_i32 s72, 0x3ff
	s_cselect_b64 s[38:39], -1, 0
	s_and_b64 vcc, exec, s[38:39]
	s_waitcnt vmcnt(1)
	v_cvt_pk_bf16_f32 v82, v82, v83
	s_waitcnt vmcnt(0)
	v_cvt_pk_bf16_f32 v80, v92, v93
	v_cvt_pk_bf16_f32 v81, v94, v95
	v_cvt_pk_bf16_f32 v83, v84, v85
	global_load_dwordx4 v[92:95], v[86:87], off offset:144
	s_nop 0
	global_load_dwordx4 v[84:87], v[86:87], off offset:128
	s_waitcnt lgkmcnt(0)
	s_barrier
	s_waitcnt vmcnt(0)
	v_cvt_pk_bf16_f32 v84, v84, v85
	v_cvt_pk_bf16_f32 v85, v86, v87
	v_cvt_pk_bf16_f32 v87, v94, v95
	v_cvt_pk_bf16_f32 v86, v92, v93
	ds_read_b128 v[212:215], v171 offset:40960
	ds_read_b128 v[216:219], v172 offset:40960
	ds_read_b128 v[220:223], v169
	ds_read_b128 v[224:227], v168
	ds_read_b128 v[228:231], v169 offset:57344
	ds_read_b128 v[232:235], v168 offset:57344
	ds_read_b128 v[236:239], v180
	ds_read_b128 v[240:243], v176
	ds_read_b128 v[244:247], v180 offset:57344
	ds_read_b128 v[248:251], v176 offset:57344
	s_waitcnt lgkmcnt(4)
	v_mfma_f32_16x16x32_bf16 v[196:199], v[220:223], v[80:83], 0
	v_mfma_f32_16x16x32_bf16 v[196:199], v[224:227], v[84:87], v[196:199]
	v_mfma_f32_16x16x32_bf16 v[196:199], v[228:231], v[212:215], v[196:199]
	v_mfma_f32_16x16x32_bf16 v[196:199], v[232:235], v[216:219], v[196:199]
	ds_read_b128 v[220:223], v178
	ds_read_b128 v[224:227], v175
	ds_read_b128 v[228:231], v178 offset:57344
	ds_read_b128 v[232:235], v175 offset:57344
	s_waitcnt lgkmcnt(4)
	v_mfma_f32_16x16x32_bf16 v[200:203], v[236:239], v[80:83], 0
	v_mfma_f32_16x16x32_bf16 v[200:203], v[240:243], v[84:87], v[200:203]
	v_mfma_f32_16x16x32_bf16 v[200:203], v[244:247], v[212:215], v[200:203]
	v_mfma_f32_16x16x32_bf16 v[200:203], v[248:251], v[216:219], v[200:203]
	ds_read_b128 v[236:239], v121
	ds_read_b128 v[240:243], v120
	ds_read_b128 v[244:247], v121 offset:57344
	ds_read_b128 v[248:251], v120 offset:57344
	s_waitcnt lgkmcnt(4)
	v_mfma_f32_16x16x32_bf16 v[204:207], v[220:223], v[80:83], 0
	v_mfma_f32_16x16x32_bf16 v[204:207], v[224:227], v[84:87], v[204:207]
	v_mfma_f32_16x16x32_bf16 v[204:207], v[228:231], v[212:215], v[204:207]
	v_mfma_f32_16x16x32_bf16 v[204:207], v[232:235], v[216:219], v[204:207]
	s_waitcnt lgkmcnt(0)
	v_mfma_f32_16x16x32_bf16 v[208:211], v[236:239], v[80:83], 0
	v_mfma_f32_16x16x32_bf16 v[208:211], v[240:243], v[84:87], v[208:211]
	v_mfma_f32_16x16x32_bf16 v[208:211], v[244:247], v[212:215], v[208:211]
	v_mfma_f32_16x16x32_bf16 v[208:211], v[248:251], v[216:219], v[208:211]
	v_lshl_add_u32 v93, v194, 10, v107
	v_lshlrev_b32_e32 v92, 6, v192
	ds_read_b128 v[98:101], v169 offset:49152
	ds_read_b128 v[102:105], v171 offset:8192
	ds_read_b128 v[220:223], v168 offset:49152
	ds_read_b128 v[224:227], v172 offset:8192
	s_waitcnt lgkmcnt(2)
	v_mfma_f32_16x16x32_bf16 v[94:97], v[98:101], v[102:105], v[196:199]
	s_waitcnt lgkmcnt(0)
	v_mfma_f32_16x16x32_bf16 v[94:97], v[220:223], v[224:227], v[94:97]
	s_nop 7
	ds_write2st64_b32 v93, v94, v95 offset1:1
	ds_write2st64_b32 v93, v96, v97 offset0:2 offset1:3
	s_waitcnt lgkmcnt(0)
	v_lshl_add_u32 v94, v194, 8, v107
	v_add_u32_e32 v95, v0, v92
	ds_read2st64_b32 v[100:101], v94 offset1:8
	ds_read2_b32 v[102:103], v95 offset1:4
	ds_read2_b32 v[104:105], v95 offset0:8 offset1:12
	s_waitcnt lgkmcnt(1)
	v_mfma_f32_16x16x4_f32 v[96:99], v102, v100, 0
	v_lshl_add_u32 v95, v106, 8, v107
	ds_read_b32 v100, v95
	s_waitcnt lgkmcnt(0)
	v_mfma_f32_16x16x4_f32 v[96:99], v103, v100, v[96:99]
	ds_read_b32 v100, v94 offset:3072
	v_mfma_f32_16x16x4_f32 v[96:99], v104, v101, v[96:99]
	s_waitcnt lgkmcnt(0)
	v_mfma_f32_16x16x4_f32 v[96:99], v105, v100, v[96:99]
	v_cvt_pk_bf16_f32 v96, v96, v97
	v_cvt_pk_bf16_f32 v97, v98, v99
	s_nop 9
	ds_write_b64 v91, v[96:97] offset:8192
	s_waitcnt lgkmcnt(0)
	v_lshl_add_u32 v91, v154, 6, v0
	ds_read_b128 v[100:103], v180 offset:49152
	ds_read_b128 v[104:107], v171 offset:8192
	ds_read_b128 v[220:223], v176 offset:49152
	ds_read_b128 v[224:227], v172 offset:8192
	s_waitcnt lgkmcnt(2)
	v_mfma_f32_16x16x32_bf16 v[96:99], v[100:103], v[104:107], v[200:203]
	s_waitcnt lgkmcnt(0)
	v_mfma_f32_16x16x32_bf16 v[96:99], v[220:223], v[224:227], v[96:99]
	s_nop 7
	ds_write2st64_b32 v93, v96, v97 offset1:1
	ds_write2st64_b32 v93, v98, v99 offset0:2 offset1:3
	s_waitcnt lgkmcnt(0)
	ds_read2st64_b32 v[100:101], v94 offset1:8
	ds_read2_b32 v[102:103], v91 offset1:4
	ds_read2_b32 v[104:105], v91 offset0:8 offset1:12
	s_waitcnt lgkmcnt(1)
	v_mfma_f32_16x16x4_f32 v[96:99], v102, v100, 0
	ds_read_b32 v91, v95
	s_waitcnt lgkmcnt(0)
	v_mfma_f32_16x16x4_f32 v[96:99], v103, v91, v[96:99]
	ds_read_b32 v91, v94 offset:3072
	v_mfma_f32_16x16x4_f32 v[96:99], v104, v101, v[96:99]
	s_waitcnt lgkmcnt(0)
	v_mfma_f32_16x16x4_f32 v[96:99], v105, v91, v[96:99]
	v_cvt_pk_bf16_f32 v96, v96, v97
	v_cvt_pk_bf16_f32 v97, v98, v99
	s_nop 9
	ds_write_b64 v90, v[96:97] offset:8192
	s_waitcnt lgkmcnt(0)
	ds_read_b128 v[100:103], v178 offset:49152
	ds_read_b128 v[104:107], v171 offset:8192
	ds_read_b128 v[220:223], v175 offset:49152
	ds_read_b128 v[224:227], v172 offset:8192
	s_waitcnt lgkmcnt(2)
	v_mfma_f32_16x16x32_bf16 v[96:99], v[100:103], v[104:107], v[204:207]
	s_waitcnt lgkmcnt(0)
	v_mfma_f32_16x16x32_bf16 v[96:99], v[220:223], v[224:227], v[96:99]
	s_nop 7
	ds_write2st64_b32 v93, v96, v97 offset1:1
	ds_write2st64_b32 v93, v98, v99 offset0:2 offset1:3
	s_waitcnt lgkmcnt(0)
	v_lshl_add_u32 v96, v151, 6, v0
	ds_read2st64_b32 v[90:91], v94 offset1:8
	ds_read2_b32 v[100:101], v96 offset1:4
	ds_read2_b32 v[102:103], v96 offset0:8 offset1:12
	s_waitcnt lgkmcnt(1)
	v_mfma_f32_16x16x4_f32 v[96:99], v100, v90, 0
	ds_read_b32 v90, v95
	v_lshl_add_u32 v0, v150, 6, v0
	s_waitcnt lgkmcnt(0)
	v_mfma_f32_16x16x4_f32 v[96:99], v101, v90, v[96:99]
	ds_read_b32 v90, v94 offset:3072
	v_mfma_f32_16x16x4_f32 v[96:99], v102, v91, v[96:99]
	s_waitcnt lgkmcnt(0)
	v_mfma_f32_16x16x4_f32 v[96:99], v103, v90, v[96:99]
	v_cvt_pk_bf16_f32 v90, v96, v97
	v_cvt_pk_bf16_f32 v91, v98, v99
	ds_write_b64 v3, v[90:91] offset:8192
	s_waitcnt lgkmcnt(0)
	s_nop 8
	ds_read_b128 v[84:87], v121 offset:49152
	ds_read_b128 v[96:99], v171 offset:8192
	ds_read_b128 v[220:223], v120 offset:49152
	ds_read_b128 v[224:227], v172 offset:8192
	s_waitcnt lgkmcnt(2)
	v_mfma_f32_16x16x32_bf16 v[80:83], v[84:87], v[96:99], v[208:211]
	s_waitcnt lgkmcnt(0)
	v_mfma_f32_16x16x32_bf16 v[80:83], v[220:223], v[224:227], v[80:83]
	s_nop 7
	ds_write2st64_b32 v93, v80, v81 offset1:1
	ds_write2st64_b32 v93, v82, v83 offset0:2 offset1:3
	s_waitcnt lgkmcnt(0)
	ds_read2st64_b32 v[84:85], v94 offset1:8
	ds_read2_b32 v[86:87], v0 offset1:4
	ds_read2_b32 v[90:91], v0 offset0:8 offset1:12
	s_waitcnt lgkmcnt(1)
	v_mfma_f32_16x16x4_f32 v[80:83], v86, v84, 0
	ds_read_b32 v0, v95
	s_waitcnt lgkmcnt(0)
	v_mfma_f32_16x16x4_f32 v[80:83], v87, v0, v[80:83]
	ds_read_b32 v0, v94 offset:3072
	v_mfma_f32_16x16x4_f32 v[80:83], v90, v85, v[80:83]
	s_waitcnt lgkmcnt(0)
	v_mfma_f32_16x16x4_f32 v[80:83], v91, v0, v[80:83]
	v_cvt_pk_bf16_f32 v80, v80, v81
	v_cvt_pk_bf16_f32 v81, v82, v83
	s_nop 9
	ds_write_b64 v2, v[80:81] offset:8192
	s_waitcnt lgkmcnt(0)
	s_waitcnt lgkmcnt(0)
	s_barrier
	s_cbranch_vccnz .LBB0_1048
	v_mov_b32_e32 v80, v177
	s_ashr_i32 s24, s72, 3
	s_lshl_b32 s0, s24, 6
	v_mul_hi_i32 v81, v80, s22
	s_and_b32 s28, s0, s64
	v_lshrrev_b32_e32 v82, 31, v81
	v_ashrrev_i32_e32 v2, 2, v81
	s_add_i32 s28, s28, -1
	v_add_u32_e32 v42, v2, v82
	s_add_i32 s25, s70, s0
	v_add_u32_e32 v2, s28, v42
	s_movk_i32 s0, 0x630
	v_lshlrev_b32_e32 v0, 3, v80
	v_cmp_gt_i32_e32 vcc, s0, v80
	v_cmp_gt_u32_e64 s[0:1], s69, v2
	v_mov_b32_e32 v6, v1
	v_mov_b32_e32 v7, v1
	v_and_b32_e32 v0, 56, v0
	s_and_b64 s[40:41], vcc, s[0:1]
	v_mov_b32_e32 v4, v1
	v_mov_b32_e32 v5, v1
	s_movk_i32 s0, 0xffe8
	v_mov_b64_e32 v[10:11], v[6:7]
	s_and_b32 s5, s71, 0x1c0
	v_mul_lo_u32 v43, v42, s0
	v_lshlrev_b32_e32 v40, 1, v0
	v_mov_b64_e32 v[8:9], v[4:5]
	s_and_saveexec_b64 s[0:1], s[40:41]
	s_cbranch_execz .LBB0_1037
	v_add_u32_e32 v0, s25, v42
	v_mov_b64_e32 v[2:3], s[16:17]
	v_mad_i64_i32 v[2:3], s[40:41], v0, s12, v[2:3]
	v_add_lshl_u32 v0, v43, v80, 6
	v_and_b32_e32 v8, 0xfffffe00, v0
	v_ashrrev_i32_e32 v9, 31, v8
	v_lshl_add_u64 v[2:3], v[8:9], 1, v[2:3]
	s_lshl_b32 s10, s5, 1
	v_lshl_add_u64 v[2:3], v[2:3], 0, s[10:11]
	v_mov_b32_e32 v41, v1
	v_lshl_add_u64 v[2:3], v[2:3], 0, v[40:41]
	v_add_co_u32_e32 v2, vcc, 0x1000, v2
	s_nop 1
	v_addc_co_u32_e32 v3, vcc, 0, v3, vcc
	global_load_dwordx4 v[8:11], v[2:3], off offset:1024

.LBB0_1048:
	v_lshlrev_b32_e32 v0, 2, v193
	v_lshl_add_u64 v[2:3], v[88:89], 0, v[0:1]
	v_lshlrev_b32_e32 v0, 2, v92
	v_lshl_add_u64 v[2:3], v[2:3], 0, v[0:1]
	v_and_b32_e32 v196, 63, v177
	v_lshlrev_b32_e32 v196, 8, v196
	v_mov_b32_e32 v197, 0
	v_lshl_add_u64 v[196:197], v[88:89], 0, v[196:197]
	global_load_dword v198, v[196:197], off
	global_load_dword v199, v[196:197], off offset:128
	global_load_dwordx4 v[80:83], v[2:3], off offset:16
	global_load_dwordx4 v[84:87], v[2:3], off
	s_mov_b64 s[0:1], 0x1000
	v_add_co_u32_e32 v116, vcc, s21, v2
	v_lshl_add_u64 v[104:105], v[2:3], 0, s[0:1]
	s_nop 0
	v_addc_co_u32_e32 v117, vcc, 0, v3, vcc
	s_movk_i32 s0, 0x2000
	v_add_co_u32_e32 v120, vcc, s0, v2
	s_mov_b64 s[0:1], 0x1080
	s_nop 0
	v_addc_co_u32_e32 v121, vcc, 0, v3, vcc
	v_lshl_add_u64 v[118:119], v[2:3], 0, s[0:1]
	s_mov_b64 s[0:1], 0x2000
	s_waitcnt vmcnt(0)
	v_cvt_pk_bf16_f32 v84, v84, v85
	v_cvt_pk_bf16_f32 v85, v86, v87
	v_cvt_pk_bf16_f32 v86, v80, v81
	v_cvt_pk_bf16_f32 v87, v82, v83
	global_load_dwordx4 v[80:83], v[2:3], off offset:144
	global_load_dwordx4 v[88:91], v[2:3], off offset:128
	ds_read_b128 v[108:111], v171 offset:24576
	ds_read_b128 v[112:115], v172 offset:24576
	s_waitcnt vmcnt(0)
	v_cvt_pk_bf16_f32 v88, v88, v89
	v_cvt_pk_bf16_f32 v89, v90, v91
	v_cvt_pk_bf16_f32 v90, v80, v81
	v_cvt_pk_bf16_f32 v91, v82, v83
	s_waitcnt lgkmcnt(1)
	v_mfma_f32_16x16x32_bf16 v[80:83], v[108:111], v[84:87], 0
	ds_read_b128 v[96:99], v171 offset:32768
	ds_read_b128 v[84:87], v169 offset:40960
	s_waitcnt lgkmcnt(2)
	v_mfma_f32_16x16x32_bf16 v[80:83], v[112:115], v[88:91], v[80:83]
	s_waitcnt lgkmcnt(0)
	v_mfma_f32_16x16x32_bf16 v[80:83], v[96:99], v[84:87], v[80:83]
	ds_read_b128 v[92:95], v172 offset:32768
	ds_read_b128 v[84:87], v168 offset:40960
	s_waitcnt lgkmcnt(0)
	v_mfma_f32_16x16x32_bf16 v[80:83], v[92:95], v[84:87], v[80:83]
	ds_read_b128 v[88:91], v171 offset:16384
	ds_read_b128 v[84:87], v169 offset:8192
	s_waitcnt lgkmcnt(0)
	v_mfma_f32_16x16x32_bf16 v[80:83], v[88:91], v[84:87], v[80:83]
	ds_read_b128 v[84:87], v172 offset:16384
	ds_read_b128 v[100:103], v168 offset:8192
	s_waitcnt lgkmcnt(0)
	v_mfma_f32_16x16x32_bf16 v[80:83], v[84:87], v[100:103], v[80:83]
	global_load_dwordx4 v[100:103], v[120:121], off offset:-4096
	s_nop 0
	global_load_dwordx4 v[104:107], v[104:105], off offset:16
	s_waitcnt vmcnt(1)
	v_cvt_pk_bf16_f32 v100, v100, v101
	v_cvt_pk_bf16_f32 v101, v102, v103
	s_waitcnt vmcnt(0)
	v_cvt_pk_bf16_f32 v102, v104, v105
	v_cvt_pk_bf16_f32 v103, v106, v107
	global_load_dwordx4 v[104:107], v[116:117], off offset:128
	s_nop 0
	global_load_dwordx4 v[116:119], v[118:119], off offset:16
	v_mfma_f32_16x16x32_bf16 v[100:103], v[108:111], v[100:103], 0
	s_waitcnt vmcnt(1)
	v_cvt_pk_bf16_f32 v104, v104, v105
	v_cvt_pk_bf16_f32 v105, v106, v107
	s_waitcnt vmcnt(0)
	v_cvt_pk_bf16_f32 v106, v116, v117
	v_cvt_pk_bf16_f32 v107, v118, v119
	v_lshl_add_u64 v[116:117], v[2:3], 0, s[0:1]
	v_mfma_f32_16x16x32_bf16 v[100:103], v[112:115], v[104:107], v[100:103]
	ds_read_b128 v[104:107], v169 offset:43008
	s_mov_b64 s[0:1], 0x2080
	v_lshl_add_u64 v[122:123], v[2:3], 0, s[0:1]
	s_waitcnt lgkmcnt(0)
	v_mfma_f32_16x16x32_bf16 v[100:103], v[96:99], v[104:107], v[100:103]
	ds_read_b128 v[104:107], v168 offset:43008
	s_mov_b64 s[0:1], 0x3000
	s_waitcnt lgkmcnt(0)
	v_mfma_f32_16x16x32_bf16 v[100:103], v[92:95], v[104:107], v[100:103]
	ds_read_b128 v[104:107], v169 offset:10240
	s_waitcnt lgkmcnt(0)
	v_mfma_f32_16x16x32_bf16 v[100:103], v[88:91], v[104:107], v[100:103]
	ds_read_b128 v[104:107], v168 offset:10240
	s_waitcnt lgkmcnt(0)
	v_mfma_f32_16x16x32_bf16 v[100:103], v[84:87], v[104:107], v[100:103]
	global_load_dwordx4 v[104:107], v[120:121], off
	s_nop 0
	global_load_dwordx4 v[116:119], v[116:117], off offset:16
	s_waitcnt vmcnt(1)
	v_cvt_pk_bf16_f32 v104, v104, v105
	v_cvt_pk_bf16_f32 v105, v106, v107
	s_waitcnt vmcnt(0)
	v_cvt_pk_bf16_f32 v106, v116, v117
	v_cvt_pk_bf16_f32 v107, v118, v119
	global_load_dwordx4 v[116:119], v[120:121], off offset:128
	s_nop 0
	global_load_dwordx4 v[120:123], v[122:123], off offset:16
	v_mfma_f32_16x16x32_bf16 v[104:107], v[108:111], v[104:107], 0
	s_waitcnt vmcnt(1)
	v_cvt_pk_bf16_f32 v116, v116, v117
	v_cvt_pk_bf16_f32 v117, v118, v119
	s_waitcnt vmcnt(0)
	v_cvt_pk_bf16_f32 v118, v120, v121
	v_cvt_pk_bf16_f32 v119, v122, v123
	v_lshl_add_u64 v[120:121], v[2:3], 0, s[0:1]
	v_mfma_f32_16x16x32_bf16 v[104:107], v[112:115], v[116:119], v[104:107]
	ds_read_b128 v[116:119], v169 offset:45056
	s_movk_i32 s0, 0x3000
	v_add_co_u32_e32 v142, vcc, s0, v2
	s_waitcnt lgkmcnt(0)
	v_mfma_f32_16x16x32_bf16 v[104:107], v[96:99], v[116:119], v[104:107]
	ds_read_b128 v[116:119], v168 offset:45056
	v_addc_co_u32_e32 v143, vcc, 0, v3, vcc
	s_waitcnt lgkmcnt(0)
	v_mfma_f32_16x16x32_bf16 v[104:107], v[92:95], v[116:119], v[104:107]
	ds_read_b128 v[116:119], v169 offset:12288
	s_mov_b64 s[0:1], 0x3080
	v_lshl_add_u64 v[2:3], v[2:3], 0, s[0:1]
	s_waitcnt lgkmcnt(0)
	v_mfma_f32_16x16x32_bf16 v[104:107], v[88:91], v[116:119], v[104:107]
	ds_read_b128 v[116:119], v168 offset:12288
	s_movk_i32 s0, 0xff84
	v_mad_i32_i24 v0, v192, s0, v167
	s_waitcnt lgkmcnt(0)
	v_mfma_f32_16x16x32_bf16 v[104:107], v[84:87], v[116:119], v[104:107]
	global_load_dwordx4 v[116:119], v[142:143], off
	s_nop 0
	global_load_dwordx4 v[120:123], v[120:121], off offset:16
	s_waitcnt vmcnt(1)
	v_cvt_pk_bf16_f32 v116, v116, v117
	v_cvt_pk_bf16_f32 v117, v118, v119
	s_waitcnt vmcnt(0)
	v_cvt_pk_bf16_f32 v118, v120, v121
	v_cvt_pk_bf16_f32 v119, v122, v123
	global_load_dwordx4 v[120:123], v[142:143], off offset:128
	global_load_dwordx4 v[170:173], v[2:3], off offset:16
	v_mfma_f32_16x16x32_bf16 v[108:111], v[108:111], v[116:119], 0
	v_cndmask_b32_e64 v2, v158, v144, s[36:37]
	v_lshl_add_u32 v2, v2, 8, v0
	v_cndmask_b32_e64 v3, v159, v145, s[36:37]
	v_lshl_add_u32 v3, v3, 8, v0
	v_add_u32_e32 v2, 0xc000, v2
	v_add_u32_e32 v3, 0xc000, v3
	s_waitcnt vmcnt(1)
	v_cvt_pk_bf16_f32 v120, v120, v121
	v_cvt_pk_bf16_f32 v121, v122, v123
	s_waitcnt vmcnt(0)
	v_cvt_pk_bf16_f32 v122, v170, v171
	v_cvt_pk_bf16_f32 v123, v172, v173
	s_nop 0
	v_mfma_f32_16x16x32_bf16 v[108:111], v[112:115], v[120:123], v[108:111]
	ds_read_b128 v[112:115], v169 offset:47104
	s_waitcnt lgkmcnt(0)
	v_mfma_f32_16x16x32_bf16 v[96:99], v[96:99], v[112:115], v[108:111]
	s_nop 4
	ds_read_b128 v[108:111], v168 offset:47104
	s_waitcnt lgkmcnt(0)
	v_mfma_f32_16x16x32_bf16 v[92:95], v[92:95], v[108:111], v[96:99]
	s_nop 2
	ds_read_b128 v[96:99], v169 offset:14336
	s_waitcnt lgkmcnt(0)
	v_mfma_f32_16x16x32_bf16 v[88:91], v[88:91], v[96:99], v[92:95]
	s_nop 2
	ds_read_b128 v[92:95], v168 offset:14336
	s_waitcnt lgkmcnt(0)
	s_waitcnt lgkmcnt(0)
	v_mfma_f32_16x16x32_bf16 v[84:87], v[84:87], v[92:95], v[88:91]
	s_nop 2
	v_cndmask_b32_e64 v88, v164, v146, s[36:37]
	v_cndmask_b32_e64 v89, v165, v147, s[36:37]
	v_lshl_add_u32 v88, v88, 8, v0
	v_lshl_add_u32 v0, v89, 8, v0
	s_barrier
	ds_write2_b32 v2, v80, v100 offset1:16
	v_add_u32_e32 v80, 0xc000, v88
	v_add_u32_e32 v0, 0xc000, v0
	ds_write2_b32 v3, v81, v101 offset1:16
	ds_write2_b32 v80, v82, v102 offset1:16
	ds_write2_b32 v0, v83, v103 offset1:16
	ds_write2_b32 v2, v104, v84 offset0:32 offset1:48
	ds_write2_b32 v3, v105, v85 offset0:32 offset1:48
	ds_write2_b32 v80, v106, v86 offset0:32 offset1:48
	ds_write2_b32 v0, v107, v87 offset0:32 offset1:48
	s_waitcnt lgkmcnt(0)
	s_barrier
	s_and_saveexec_b64 s[40:41], s[36:37]
	s_cbranch_execz .LBB0_819
	v_lshlrev_b32_e32 v0, 6, v144
	v_or_b32_e32 v2, v0, v192
	v_lshlrev_b32_e32 v3, 2, v2
	v_add_u32_e32 v2, 0, v3
	v_add_u32_e32 v3, s30, v3
	ds_read_b32 v2, v2 offset:49152
	ds_read_b32 v86, v3
	ds_read_b32 v114, v148 offset:49344
	v_or_b32_e32 v3, v152, v192
	v_lshlrev_b32_e32 v3, 2, v3
	v_add_u32_e32 v80, 0, v3
	v_add_u32_e32 v3, s30, v3
	ds_read_b32 v80, v80 offset:49152
	ds_read_b32 v88, v3
	v_or_b32_e32 v3, v155, v192
	v_lshlrev_b32_e32 v3, 2, v3
	v_add_u32_e32 v81, 0, v3
	v_add_u32_e32 v3, s30, v3
	ds_read_b32 v82, v81 offset:49152
	ds_read_b32 v90, v3
	v_or_b32_e32 v3, v157, v192
	v_lshlrev_b32_e32 v3, 2, v3
	v_add_u32_e32 v81, 0, v3
	v_add_u32_e32 v3, s30, v3
	ds_read_b32 v84, v81 offset:49152
	ds_read_b32 v92, v3
	v_or_b32_e32 v3, v0, v154
	v_lshl_add_u32 v3, v3, 2, s30
	ds_read_b32 v87, v3
	ds_read_b32 v116, v149 offset:49344
	v_or_b32_e32 v3, v152, v154
	v_lshl_add_u32 v3, v3, 2, s30
	ds_read_b32 v89, v3
	ds_read_b32 v110, v153 offset:49344
	v_or_b32_e32 v3, v155, v154
	v_lshl_add_u32 v3, v3, 2, s30
	ds_read_b32 v91, v3
	ds_read_b32 v100, v156 offset:49344
	v_or_b32_e32 v3, v157, v154
	v_lshl_add_u32 v3, v3, 2, s30
	ds_read_b32 v93, v3
	v_or_b32_e32 v3, v0, v151
	v_or_b32_e32 v0, v0, v150
	v_lshl_add_u32 v0, v0, 2, s30
	ds_read_b32 v106, v0
	v_or_b32_e32 v0, v152, v150
	v_lshl_add_u32 v3, v3, 2, s30
	v_lshl_add_u32 v0, v0, 2, s30
	ds_read_b32 v107, v3
	ds_read_b32 v112, v0
	v_or_b32_e32 v3, v152, v151
	v_or_b32_e32 v0, v155, v150
	v_lshl_add_u32 v3, v3, 2, s30
	v_lshl_add_u32 v0, v0, 2, s30
	ds_read_b32 v113, v3
	ds_read_b32 v102, v0
	v_or_b32_e32 v3, v155, v151
	v_or_b32_e32 v0, v157, v150
	v_lshl_add_u32 v3, v3, 2, s30
	v_lshl_add_u32 v0, v0, 2, s30
	ds_read_b32 v103, v3
	ds_read_b32 v96, v0
	v_or_b32_e32 v3, v157, v151
	v_lshl_add_u32 v3, v3, 2, s30
	ds_read_b32 v97, v3
	v_and_b32_e32 v3, 64, v179
	v_xor_b32_e32 v0, 1, v179
	v_add_u32_e32 v3, 64, v3
	v_cmp_lt_i32_e32 vcc, v0, v3
	v_add_u32_e32 v81, 0xc000, v148
	ds_read2_b32 v[104:105], v81 offset0:16 offset1:32
	v_cndmask_b32_e32 v0, v179, v0, vcc
	v_lshlrev_b32_e32 v118, 2, v0
	v_xor_b32_e32 v0, 2, v179
	v_cmp_lt_i32_e32 vcc, v0, v3
	s_waitcnt lgkmcnt(0)
	v_mov_b32_e32 v115, v105
	v_add_u32_e32 v81, 0xc000, v149
	v_cndmask_b32_e32 v0, v179, v0, vcc
	v_lshlrev_b32_e32 v119, 2, v0
	v_xor_b32_e32 v0, 4, v179
	v_cmp_lt_i32_e32 vcc, v0, v3
	v_pk_add_f32 v[114:115], v[114:115], v[106:107]
	ds_read2_b32 v[108:109], v81 offset0:16 offset1:32
	v_cndmask_b32_e32 v0, v179, v0, vcc
	v_lshlrev_b32_e32 v120, 2, v0
	v_xor_b32_e32 v0, 8, v179
	v_cmp_lt_i32_e32 vcc, v0, v3
	v_mov_b32_e32 v3, v104
	v_pk_add_f32 v[2:3], v[2:3], v[86:87]
	v_cndmask_b32_e32 v0, v179, v0, vcc
	v_lshlrev_b32_e32 v121, 2, v0
	v_add_f32_e32 v0, 0, v2
	v_add_f32_e32 v0, v0, v3
	v_add_u32_e32 v81, 0xc000, v153
	v_add_f32_e32 v0, v0, v115
	ds_read2_b32 v[98:99], v81 offset0:16 offset1:32
	v_add_u32_e32 v81, 0xc000, v156
	v_add_f32_e32 v0, v0, v114
	ds_read2_b32 v[94:95], v81 offset0:16 offset1:32
	s_nop 1
	v_mov_b32_dpp v81, v0 quad_perm:[1,0,3,2] row_mask:0xf bank_mask:0xf
	s_waitcnt lgkmcnt(2)
	v_mov_b32_e32 v117, v109
	v_pk_add_f32 v[112:113], v[116:117], v[112:113]
	s_waitcnt lgkmcnt(1)
	v_mov_b32_e32 v111, v99
	v_pk_add_f32 v[102:103], v[110:111], v[102:103]
	s_waitcnt lgkmcnt(0)
	v_add_f32_e32 v0, v0, v81
	s_nop 1
	v_mov_b32_dpp v81, v0 quad_perm:[2,3,0,1] row_mask:0xf bank_mask:0xf
	v_mov_b32_e32 v101, v95
	v_pk_add_f32 v[96:97], v[100:101], v[96:97]
	s_mov_b32 s0, 0x3a27c5ac
	s_mov_b32 s6, 0x3c800000
	s_waitcnt lgkmcnt(0)
	v_add_f32_e32 v0, v0, v81
	s_nop 1
	v_mov_b32_dpp v81, v0 row_shl:4 row_mask:0xf bank_mask:0x5
	s_nop 1
	v_mov_b32_dpp v81, v0 row_shr:4 row_mask:0xf bank_mask:0xa
	v_readlane_b32 s44, v252, 35
	v_readlane_b32 s45, v252, 36
	v_readlane_b32 s46, v252, 37
	v_readlane_b32 s47, v252, 38
	s_waitcnt lgkmcnt(0)
	v_add_f32_e32 v0, v0, v81
	s_nop 1
	v_mov_b32_dpp v81, v0 row_shl:8 row_mask:0xf bank_mask:0x3
	s_nop 1
	v_mov_b32_dpp v81, v0 row_shr:8 row_mask:0xf bank_mask:0xc
	v_readlane_b32 s48, v252, 39
	v_readlane_b32 s49, v252, 40
	v_readlane_b32 s50, v252, 41
	v_readlane_b32 s51, v252, 42
	s_waitcnt lgkmcnt(0)
	v_add_f32_e32 v0, v0, v81
	v_mov_b32_e32 v81, v108
	v_mul_f32_e32 v0, 0x3c800000, v0
	v_pk_add_f32 v[80:81], v[80:81], v[88:89]
	v_pk_add_f32 v[86:87], v[2:3], v[0:1] op_sel_hi:[1,0] neg_lo:[0,1] neg_hi:[0,1]
	v_pk_add_f32 v[2:3], v[114:115], v[0:1] op_sel_hi:[1,0] neg_lo:[0,1] neg_hi:[0,1]
	v_add_f32_e32 v0, 0, v80
	v_add_f32_e32 v0, v0, v81
	v_add_f32_e32 v0, v0, v113
	v_add_f32_e32 v0, v0, v112
	s_nop 1
	v_mov_b32_dpp v83, v0 quad_perm:[1,0,3,2] row_mask:0xf bank_mask:0xf
	v_pk_mul_f32 v[106:107], v[86:87], v[86:87]
	v_pk_mul_f32 v[104:105], v[2:3], v[2:3]
	v_mov_b32_e32 v101, v106
	v_readlane_b32 s52, v252, 43
	s_waitcnt lgkmcnt(0)
	v_add_f32_e32 v0, v0, v83
	s_nop 1
	v_mov_b32_dpp v83, v0 quad_perm:[2,3,0,1] row_mask:0xf bank_mask:0xf
	v_readlane_b32 s53, v252, 44
	v_readlane_b32 s54, v252, 45
	v_readlane_b32 s55, v252, 46
	v_readlane_b32 s56, v252, 47
	s_waitcnt lgkmcnt(0)
	v_add_f32_e32 v0, v0, v83
	s_nop 1
	v_mov_b32_dpp v83, v0 row_shl:4 row_mask:0xf bank_mask:0x5
	s_nop 1
	v_mov_b32_dpp v83, v0 row_shr:4 row_mask:0xf bank_mask:0xa
	v_readlane_b32 s57, v252, 48
	s_mov_b64 s[44:45], s[48:49]
	s_mov_b64 s[46:47], s[50:51]
	s_mov_b64 s[48:49], s[52:53]
	s_waitcnt lgkmcnt(0)
	v_add_f32_e32 v0, v0, v83
	s_nop 1
	v_mov_b32_dpp v83, v0 row_shl:8 row_mask:0xf bank_mask:0x3
	s_nop 1
	v_mov_b32_dpp v83, v0 row_shr:8 row_mask:0xf bank_mask:0xc
	s_mov_b64 s[50:51], s[54:55]
	s_mov_b64 s[52:53], s[56:57]
	v_readlane_b32 s5, v254, 59
	s_lshl_b32 s4, s4, 6
	s_waitcnt lgkmcnt(0)
	v_add_f32_e32 v0, v0, v83
	v_mov_b32_e32 v83, v98
	v_mul_f32_e32 v0, 0x3c800000, v0
	v_pk_add_f32 v[82:83], v[82:83], v[90:91]
	v_pk_add_f32 v[88:89], v[80:81], v[0:1] op_sel_hi:[1,0] neg_lo:[0,1] neg_hi:[0,1]
	v_pk_add_f32 v[80:81], v[112:113], v[0:1] op_sel_hi:[1,0] neg_lo:[0,1] neg_hi:[0,1]
	v_add_f32_e32 v0, 0, v82
	v_add_f32_e32 v0, v0, v83
	v_add_f32_e32 v0, v0, v103
	v_add_f32_e32 v0, v0, v102
	s_nop 1
	v_mov_b32_dpp v85, v0 quad_perm:[1,0,3,2] row_mask:0xf bank_mask:0xf
	v_pk_mul_f32 v[108:109], v[88:89], v[88:89]
	v_pk_mul_f32 v[112:113], v[80:81], v[80:81]
	v_mov_b32_e32 v100, v108
	v_mov_b32_e32 v106, v109
	s_waitcnt lgkmcnt(0)
	v_add_f32_e32 v0, v0, v85
	s_nop 1
	v_mov_b32_dpp v85, v0 quad_perm:[2,3,0,1] row_mask:0xf bank_mask:0xf
	v_pk_add_f32 v[100:101], v[100:101], v[106:107]
	s_add_i32 s4, s4, s63
	v_readlane_b32 s58, v252, 49
	v_readlane_b32 s59, v252, 50
	s_waitcnt lgkmcnt(0)
	v_add_f32_e32 v0, v0, v85
	s_nop 1
	v_mov_b32_dpp v85, v0 row_shl:4 row_mask:0xf bank_mask:0x5
	s_nop 1
	v_mov_b32_dpp v85, v0 row_shr:4 row_mask:0xf bank_mask:0xa
	s_waitcnt lgkmcnt(0)
	v_add_f32_e32 v0, v0, v85
	s_nop 1
	v_mov_b32_dpp v85, v0 row_shl:8 row_mask:0xf bank_mask:0x3
	s_nop 1
	v_mov_b32_dpp v85, v0 row_shr:8 row_mask:0xf bank_mask:0xc
	s_waitcnt lgkmcnt(0)
	v_add_f32_e32 v0, v0, v85
	v_mov_b32_e32 v85, v94
	v_mul_f32_e32 v0, 0x3c800000, v0
	v_pk_add_f32 v[84:85], v[84:85], v[92:93]
	v_pk_add_f32 v[90:91], v[82:83], v[0:1] op_sel_hi:[1,0] neg_lo:[0,1] neg_hi:[0,1]
	v_pk_add_f32 v[82:83], v[102:103], v[0:1] op_sel_hi:[1,0] neg_lo:[0,1] neg_hi:[0,1]
	v_add_f32_e32 v0, 0, v84
	v_add_f32_e32 v0, v0, v85
	v_mov_b32_e32 v102, v113
	v_mov_b32_e32 v103, v105
	v_add_f32_e32 v0, v0, v97
	v_pk_add_f32 v[100:101], v[102:103], v[100:101]
	v_mov_b32_e32 v113, v104
	v_add_f32_e32 v0, v0, v96
	v_pk_add_f32 v[100:101], v[112:113], v[100:101]
	s_nop 1
	v_mov_b32_dpp v92, v0 quad_perm:[1,0,3,2] row_mask:0xf bank_mask:0xf
	s_nop 1
	v_mov_b32_dpp v103, v101 quad_perm:[1,0,3,2] row_mask:0xf bank_mask:0xf
	s_nop 1
	v_mov_b32_dpp v102, v100 quad_perm:[1,0,3,2] row_mask:0xf bank_mask:0xf
	v_mov_b64_e32 v[104:105], s[0:1]
	v_pk_mul_f32 v[98:99], v[90:91], v[90:91]
	s_waitcnt lgkmcnt(0)
	v_add_f32_e32 v0, v0, v92
	s_nop 1
	v_mov_b32_dpp v92, v0 quad_perm:[2,3,0,1] row_mask:0xf bank_mask:0xf
	s_waitcnt lgkmcnt(0)
	v_pk_add_f32 v[100:101], v[100:101], v[102:103]
	s_nop 1
	v_mov_b32_dpp v103, v101 quad_perm:[2,3,0,1] row_mask:0xf bank_mask:0xf
	s_nop 1
	v_mov_b32_dpp v102, v100 quad_perm:[2,3,0,1] row_mask:0xf bank_mask:0xf
	v_pk_mul_f32 v[110:111], v[82:83], v[82:83]
	s_waitcnt lgkmcnt(0)
	v_add_f32_e32 v0, v0, v92
	s_nop 1
	v_mov_b32_dpp v92, v0 row_shl:4 row_mask:0xf bank_mask:0x5
	s_nop 1
	v_mov_b32_dpp v92, v0 row_shr:4 row_mask:0xf bank_mask:0xa
	s_waitcnt lgkmcnt(0)
	v_pk_add_f32 v[100:101], v[100:101], v[102:103]
	s_nop 1
	v_mov_b32_dpp v103, v101 row_shl:4 row_mask:0xf bank_mask:0x5
	s_nop 1
	v_mov_b32_dpp v103, v101 row_shr:4 row_mask:0xf bank_mask:0xa
	s_nop 1
	v_mov_b32_dpp v102, v100 row_shl:4 row_mask:0xf bank_mask:0x5
	s_nop 1
	v_mov_b32_dpp v102, v100 row_shr:4 row_mask:0xf bank_mask:0xa
	s_waitcnt lgkmcnt(0)
	v_add_f32_e32 v0, v0, v92
	s_nop 1
	v_mov_b32_dpp v92, v0 row_shl:8 row_mask:0xf bank_mask:0x3
	s_nop 1
	v_mov_b32_dpp v92, v0 row_shr:8 row_mask:0xf bank_mask:0xc
	s_waitcnt lgkmcnt(0)
	v_pk_add_f32 v[100:101], v[100:101], v[102:103]
	s_nop 1
	v_mov_b32_dpp v103, v101 row_shl:8 row_mask:0xf bank_mask:0x3
	s_nop 1
	v_mov_b32_dpp v103, v101 row_shr:8 row_mask:0xf bank_mask:0xc
	s_nop 1
	v_mov_b32_dpp v102, v100 row_shl:8 row_mask:0xf bank_mask:0x3
	s_nop 1
	v_mov_b32_dpp v102, v100 row_shr:8 row_mask:0xf bank_mask:0xc
	s_waitcnt lgkmcnt(0)
	v_add_f32_e32 v0, v0, v92
	v_mul_f32_e32 v0, 0x3c800000, v0
	v_pk_add_f32 v[92:93], v[84:85], v[0:1] op_sel_hi:[1,0] neg_lo:[0,1] neg_hi:[0,1]
	v_pk_add_f32 v[84:85], v[96:97], v[0:1] op_sel_hi:[1,0] neg_lo:[0,1] neg_hi:[0,1]
	s_waitcnt lgkmcnt(0)
	v_pk_add_f32 v[100:101], v[100:101], v[102:103]
	v_pk_mul_f32 v[94:95], v[92:93], v[92:93]
	v_pk_fma_f32 v[100:101], v[100:101], s[6:7], v[104:105] op_sel_hi:[1,0,0]
	v_pk_mul_f32 v[96:97], v[84:85], v[84:85]
	v_mul_f32_e32 v0, 0x4b800000, v101
	v_cmp_gt_f32_e64 s[0:1], s29, v101
	v_cmp_gt_f32_e32 vcc, s29, v100
	s_nop 0
	v_cndmask_b32_e64 v0, v101, v0, s[0:1]
	v_rsq_f32_e32 v0, v0
	s_nop 0
	v_mul_f32_e32 v101, 0x45800000, v0
	v_cndmask_b32_e64 v103, v0, v101, s[0:1]
	v_mul_f32_e32 v0, 0x4b800000, v100
	v_cndmask_b32_e32 v0, v100, v0, vcc
	v_rsq_f32_e32 v0, v0
	v_mov_b32_e32 v101, v98
	v_mov_b32_e32 v98, v95
	v_mul_f32_e32 v86, v86, v103
	v_mul_f32_e32 v100, 0x45800000, v0
	v_cndmask_b32_e32 v102, v0, v100, vcc
	v_mov_b32_e32 v100, v94
	v_pk_add_f32 v[94:95], v[100:101], v[98:99]
	global_load_dword v100, v190, s[50:51]
	global_load_dword v101, v190, s[52:53]
	v_mov_b32_e32 v98, v97
	v_mov_b32_e32 v99, v111
	v_pk_add_f32 v[94:95], v[98:99], v[94:95]
	v_mov_b32_e32 v97, v110
	v_pk_add_f32 v[94:95], v[96:97], v[94:95]
	s_nop 1
	v_mov_b32_dpp v97, v95 quad_perm:[1,0,3,2] row_mask:0xf bank_mask:0xf
	s_nop 1
	v_mov_b32_dpp v96, v94 quad_perm:[1,0,3,2] row_mask:0xf bank_mask:0xf
	v_mul_f32_e32 v3, v3, v103
	v_mul_f32_e32 v2, v2, v103
	s_waitcnt lgkmcnt(0)
	v_pk_add_f32 v[94:95], v[94:95], v[96:97]
	s_nop 1
	v_mov_b32_dpp v97, v95 quad_perm:[2,3,0,1] row_mask:0xf bank_mask:0xf
	s_nop 1
	v_mov_b32_dpp v96, v94 quad_perm:[2,3,0,1] row_mask:0xf bank_mask:0xf
	s_waitcnt lgkmcnt(0)
	v_pk_add_f32 v[94:95], v[94:95], v[96:97]
	s_nop 1
	v_mov_b32_dpp v97, v95 row_shl:4 row_mask:0xf bank_mask:0x5
	s_nop 1
	v_mov_b32_dpp v97, v95 row_shr:4 row_mask:0xf bank_mask:0xa
	s_nop 1
	v_mov_b32_dpp v96, v94 row_shl:4 row_mask:0xf bank_mask:0x5
	s_nop 1
	v_mov_b32_dpp v96, v94 row_shr:4 row_mask:0xf bank_mask:0xa
	s_waitcnt lgkmcnt(0)
	v_pk_add_f32 v[94:95], v[94:95], v[96:97]
	s_nop 1
	v_mov_b32_dpp v97, v95 row_shl:8 row_mask:0xf bank_mask:0x3
	s_nop 1
	v_mov_b32_dpp v97, v95 row_shr:8 row_mask:0xf bank_mask:0xc
	s_nop 1
	v_mov_b32_dpp v96, v94 row_shl:8 row_mask:0xf bank_mask:0x3
	s_nop 1
	v_mov_b32_dpp v96, v94 row_shr:8 row_mask:0xf bank_mask:0xc
	s_waitcnt lgkmcnt(0)
	v_pk_add_f32 v[94:95], v[94:95], v[96:97]
	s_nop 0
	v_pk_fma_f32 v[94:95], v[94:95], s[6:7], v[104:105] op_sel_hi:[1,0,0]
	s_waitcnt vmcnt(0)
	v_fma_f32 v86, v86, v100, v101
	v_mul_f32_e32 v0, 0x4b800000, v95
	v_cmp_gt_f32_e64 s[0:1], s29, v95
	v_cmp_gt_f32_e32 vcc, s29, v94
	s_nop 0
	v_cndmask_b32_e64 v0, v95, v0, s[0:1]
	v_rsq_f32_e32 v0, v0
	s_nop 0
	v_mul_f32_e32 v95, 0x45800000, v0
	v_cndmask_b32_e64 v105, v0, v95, s[0:1]
	v_mul_f32_e32 v0, 0x4b800000, v94
	v_cndmask_b32_e32 v0, v94, v0, vcc
	v_rsq_f32_e32 v0, v0
	v_readlane_b32 s0, v254, 38
	v_readlane_b32 s1, v254, 39
	v_mul_f32_e32 v94, 0x45800000, v0
	v_cndmask_b32_e32 v104, v0, v94, vcc
	v_lshl_add_u32 v94, v144, 2, s5
	ds_read_b32 v106, v94
	v_or_b32_e32 v94, s4, v144
	v_lshlrev_b32_e32 v0, 1, v191
	v_ashrrev_i32_e32 v95, 31, v94
	v_lshl_add_u64 v[108:109], s[0:1], 0, v[0:1]
	s_waitcnt lgkmcnt(0)
	v_fmac_f32_e32 v86, v126, v106
	v_mul_f32_e32 v68, v68, v86
	v_lshlrev_b64 v[94:95], 11, v[94:95]
	v_cvt_pk_bf16_f32 v68, v68, v68
	v_lshl_add_u64 v[96:97], v[108:109], 0, v[94:95]
	v_lshl_add_u32 v86, v145, 2, s5
	global_store_short v[96:97], v68, off
	v_mul_f32_e32 v68, v88, v102
	ds_read_b32 v88, v86
	v_fma_f32 v68, v100, v68, v101
	s_waitcnt lgkmcnt(0)
	v_fmac_f32_e32 v68, v140, v88
	v_mul_f32_e32 v68, v69, v68
	v_cvt_pk_bf16_f32 v86, v68, v68
	v_or_b32_e32 v68, s4, v145
	v_ashrrev_i32_e32 v69, 31, v68
	v_lshlrev_b64 v[96:97], 11, v[68:69]
	v_lshl_add_u64 v[68:69], v[108:109], 0, v[96:97]
	global_store_short v[68:69], v86, off
	v_lshl_add_u32 v69, v146, 2, s5
	v_mul_f32_e32 v68, v90, v105
	ds_read_b32 v90, v69
	v_fma_f32 v68, v100, v68, v101
	s_waitcnt lgkmcnt(0)
	v_fmac_f32_e32 v68, v141, v90
	v_mul_f32_e32 v68, v70, v68
	v_cvt_pk_bf16_f32 v70, v68, v68
	v_or_b32_e32 v68, s4, v146
	v_ashrrev_i32_e32 v69, 31, v68
	v_lshlrev_b64 v[98:99], 11, v[68:69]
	v_lshl_add_u64 v[68:69], v[108:109], 0, v[98:99]
	global_store_short v[68:69], v70, off
	v_mul_f32_e32 v68, v92, v104
	v_fmac_f32_e32 v101, v100, v68
	v_lshl_add_u32 v68, v147, 2, s5
	ds_read_b32 v92, v68
	s_waitcnt lgkmcnt(0)
	v_fmac_f32_e32 v101, v129, v92
	v_mul_f32_e32 v68, v71, v101
	v_cvt_pk_bf16_f32 v70, v68, v68
	v_or_b32_e32 v68, s4, v147
	v_ashrrev_i32_e32 v69, 31, v68
	v_lshlrev_b64 v[100:101], 11, v[68:69]
	v_lshl_add_u64 v[68:69], v[108:109], 0, v[100:101]
	global_store_short v[68:69], v70, off
	global_load_dword v107, v190, s[50:51] offset:64
	global_load_dword v108, v190, s[52:53] offset:64
	v_mul_f32_e32 v68, v87, v103
	v_lshl_add_u64 v[86:87], s[0:1], 0, v[96:97]
	s_waitcnt vmcnt(0)
	v_fma_f32 v68, v68, v107, v108
	v_fmac_f32_e32 v68, v128, v106
	v_mul_f32_e32 v64, v64, v68
	v_lshl_add_u64 v[68:69], s[0:1], 0, v[94:95]
	v_or_b32_e32 v94, 32, v0
	v_mov_b32_e32 v95, v1
	v_cvt_pk_bf16_f32 v64, v64, v64
	v_lshl_add_u64 v[70:71], v[68:69], 0, v[94:95]
	global_store_short v[70:71], v64, off
	v_mul_f32_e32 v64, v89, v102
	v_fma_f32 v64, v64, v107, v108
	v_fmac_f32_e32 v64, v138, v88
	v_mul_f32_e32 v64, v65, v64
	v_cvt_pk_bf16_f32 v70, v64, v64
	v_lshl_add_u64 v[64:65], v[86:87], 0, v[94:95]
	global_store_short v[64:65], v70, off
	v_mul_f32_e32 v64, v91, v105
	v_fma_f32 v64, v64, v107, v108
	v_fmac_f32_e32 v64, v139, v90
	v_mul_f32_e32 v64, v66, v64
	v_lshl_add_u64 v[70:71], s[0:1], 0, v[98:99]
	v_cvt_pk_bf16_f32 v66, v64, v64
	v_lshl_add_u64 v[64:65], v[70:71], 0, v[94:95]
	global_store_short v[64:65], v66, off
	v_mul_f32_e32 v64, v93, v104
	v_fmac_f32_e32 v108, v64, v107
	v_fmac_f32_e32 v108, v131, v92
	v_mul_f32_e32 v64, v67, v108
	v_cvt_pk_bf16_f32 v89, v64, v64
	v_lshl_add_u64 v[64:65], s[0:1], 0, v[100:101]
	v_lshl_add_u64 v[66:67], v[64:65], 0, v[94:95]
	global_store_short v[66:67], v89, off
	global_load_dword v89, v190, s[50:51] offset:128
	s_nop 0
	global_load_dword v91, v190, s[52:53] offset:128
	v_or_b32_e32 v66, 64, v0
	v_mov_b32_e32 v67, v1
	v_lshl_add_u64 v[94:95], v[68:69], 0, v[66:67]
	v_or_b32_e32 v0, 0x60, v0
	s_waitcnt vmcnt(0)
	v_fma_f32 v3, v3, v89, v91
	v_fmac_f32_e32 v3, v130, v106
	v_mul_f32_e32 v3, v72, v3
	v_cvt_pk_bf16_f32 v3, v3, v3
	global_store_short v[94:95], v3, off
	v_mul_f32_e32 v3, v81, v102
	v_fma_f32 v3, v3, v89, v91
	v_fmac_f32_e32 v3, v136, v88
	v_mul_f32_e32 v3, v73, v3
	v_cvt_pk_bf16_f32 v3, v3, v3
	v_lshl_add_u64 v[72:73], v[86:87], 0, v[66:67]
	global_store_short v[72:73], v3, off
	v_mul_f32_e32 v3, v83, v105
	v_fma_f32 v3, v3, v89, v91
	v_fmac_f32_e32 v3, v137, v90
	v_mul_f32_e32 v3, v74, v3
	v_cvt_pk_bf16_f32 v3, v3, v3
	v_lshl_add_u64 v[72:73], v[70:71], 0, v[66:67]
	global_store_short v[72:73], v3, off
	v_mul_f32_e32 v3, v85, v104
	v_fmac_f32_e32 v91, v3, v89
	v_fmac_f32_e32 v91, v133, v92
	v_mul_f32_e32 v3, v75, v91
	v_lshl_add_u64 v[66:67], v[64:65], 0, v[66:67]
	v_cvt_pk_bf16_f32 v3, v3, v3
	global_store_short v[66:67], v3, off
	global_load_dword v66, v190, s[50:51] offset:192
	s_nop 0
	global_load_dword v67, v190, s[52:53] offset:192
	s_waitcnt vmcnt(0)
	v_fma_f32 v2, v2, v66, v67
	v_fmac_f32_e32 v2, v132, v106
	v_mul_f32_e32 v2, v76, v2
	v_cvt_pk_bf16_f32 v72, v2, v2
	v_lshl_add_u64 v[2:3], v[68:69], 0, v[0:1]
	global_store_short v[2:3], v72, off
	v_mul_f32_e32 v2, v80, v102
	v_fma_f32 v2, v2, v66, v67
	v_fmac_f32_e32 v2, v134, v88
	v_mul_f32_e32 v2, v77, v2
	v_cvt_pk_bf16_f32 v68, v2, v2
	v_lshl_add_u64 v[2:3], v[86:87], 0, v[0:1]
	global_store_short v[2:3], v68, off
	v_mul_f32_e32 v2, v82, v105
	v_fma_f32 v2, v2, v66, v67
	v_fmac_f32_e32 v2, v135, v90
	v_mul_f32_e32 v2, v78, v2
	v_cvt_pk_bf16_f32 v68, v2, v2
	v_lshl_add_u64 v[2:3], v[70:71], 0, v[0:1]
	global_store_short v[2:3], v68, off
	v_mul_f32_e32 v2, v84, v104
	v_fmac_f32_e32 v67, v2, v66
	v_fmac_f32_e32 v67, v127, v92
	v_mul_f32_e32 v2, v79, v67
	v_cvt_pk_bf16_f32 v66, v2, v2
	v_lshl_add_u64 v[2:3], v[64:65], 0, v[0:1]
	global_store_short v[2:3], v66, off
	s_branch .LBB0_819
